# in_proj epilogue: transposed-V rows written as two 8-byte stores per lane after DPP quad transposes (were eight 2-byte stores)
# speedup vs baseline: 1.0114x; 1.0066x over previous
; __device__ __forceinline__ u32x4 pack8(f32x4 a, f32x4 b) { u32x4 w; w.x = cvtpk(a[0], a[1]); w.y = cvtpk(a[2], a[3]); w.z = cvtpk(b[0], b[1]); w.w = cvtpk(b[2], b[3]); return w; }
;     __device__ __forceinline__ void operator()(const pg8::f32x4 (&acc)[2][2][4][2], const pg8::Unit& u, int wr, int wc, int fr, int fq) const {
;     ...
;                         if (pn == 2 && bj == 1) {
;                             const int vc = cl;
;                             const u32x4 w = pack8(v0, v1);
;                             bf16* vt = VT + ((size_t)((vc >> 6) * (MP / 4) + (row >> 2)) * 64 + (vc & 63)) * 4 + (row & 3);
;                             vt[0] = (bf16)(w.x & 0xffff); vt[4] = (bf16)(w.x >> 16); vt[8] = (bf16)(w.y & 0xffff); vt[12] = (bf16)(w.y >> 16);
;                             vt[16] = (bf16)(w.z & 0xffff); vt[20] = (bf16)(w.z >> 16); vt[24] = (bf16)(w.w & 0xffff); vt[28] = (bf16)(w.w >> 16);
;                             float* dst = nullptr;
;                             if (row < NPT) { const int t = row % LP; if (t >= LP - 128) dst = out + O_WVP + ((size_t)((l * 8 + row / LP) * 128 + (t - (LP - 128)))) * 128 + vc; }
.LBB0_571:
	v_lshrrev_b32_e32 v82, 6, v172
	s_movk_i32 s2, 0x10c0
	v_mul_lo_u32 v88, v82, s2
	s_andn2_b64 vcc, exec, s[0:1]
	v_lshlrev_b32_e32 v80, 1, v80
	v_lshlrev_b32_e32 v82, 1, v193
	s_cbranch_vccnz .LBB0_579
	v_ashrrev_i32_e32 v83, 2, v178
	v_add_u32_e32 v86, v88, v83
	v_ashrrev_i32_e32 v87, 31, v86
	v_lshlrev_b64 v[86:87], 9, v[86:87]
	v_lshl_add_u64 v[86:87], s[8:9], 0, v[86:87]
	v_lshl_add_u64 v[86:87], v[86:87], 0, v[80:81]
	v_mov_b32_e32 v83, v81
	v_lshl_add_u64 v[86:87], v[82:83], 2, v[86:87]
	s_waitcnt vmcnt(2)
	s_waitcnt vmcnt(0)
	s_mov_b32 s0, 0xaaaaaaaa
	s_mov_b32 s1, 0xaaaaaaaa
	s_mov_b32 s2, 0xcccccccc
	s_mov_b32 s3, 0xcccccccc
	s_nop 1
	v_mov_b32_dpp v112, v60 quad_perm:[1,0,3,2] row_mask:0xf bank_mask:0xf
	v_mov_b32_dpp v113, v61 quad_perm:[1,0,3,2] row_mask:0xf bank_mask:0xf
	v_mov_b32_dpp v156, v62 quad_perm:[1,0,3,2] row_mask:0xf bank_mask:0xf
	v_mov_b32_dpp v157, v63 quad_perm:[1,0,3,2] row_mask:0xf bank_mask:0xf
	v_cndmask_b32_e64 v94, v60, v113, s[0:1]
	v_cndmask_b32_e64 v95, v112, v61, s[0:1]
	v_cndmask_b32_e64 v96, v62, v157, s[0:1]
	v_cndmask_b32_e64 v97, v156, v63, s[0:1]
	s_nop 1
	v_mov_b32_dpp v112, v94 quad_perm:[2,3,0,1] row_mask:0xf bank_mask:0xf
	v_mov_b32_dpp v113, v95 quad_perm:[2,3,0,1] row_mask:0xf bank_mask:0xf
	v_mov_b32_dpp v156, v96 quad_perm:[2,3,0,1] row_mask:0xf bank_mask:0xf
	v_mov_b32_dpp v157, v97 quad_perm:[2,3,0,1] row_mask:0xf bank_mask:0xf
	v_cndmask_b32_e64 v156, v94, v156, s[2:3]
	v_cndmask_b32_e64 v157, v95, v157, s[2:3]
	v_cndmask_b32_e64 v112, v112, v96, s[2:3]
	v_cndmask_b32_e64 v113, v113, v97, s[2:3]
	v_cvt_pk_bf16_f32 v94, v156, v157
	v_cvt_pk_bf16_f32 v95, v112, v113
	global_store_dwordx2 v[86:87], v[94:95], off
	s_nop 1
	v_mov_b32_dpp v112, v56 quad_perm:[1,0,3,2] row_mask:0xf bank_mask:0xf
	v_mov_b32_dpp v113, v57 quad_perm:[1,0,3,2] row_mask:0xf bank_mask:0xf
	v_mov_b32_dpp v156, v58 quad_perm:[1,0,3,2] row_mask:0xf bank_mask:0xf
	v_mov_b32_dpp v157, v59 quad_perm:[1,0,3,2] row_mask:0xf bank_mask:0xf
	v_cndmask_b32_e64 v94, v56, v113, s[0:1]
	v_cndmask_b32_e64 v95, v112, v57, s[0:1]
	v_cndmask_b32_e64 v96, v58, v157, s[0:1]
	v_cndmask_b32_e64 v97, v156, v59, s[0:1]
	s_nop 1
	v_mov_b32_dpp v112, v94 quad_perm:[2,3,0,1] row_mask:0xf bank_mask:0xf
	v_mov_b32_dpp v113, v95 quad_perm:[2,3,0,1] row_mask:0xf bank_mask:0xf
	v_mov_b32_dpp v156, v96 quad_perm:[2,3,0,1] row_mask:0xf bank_mask:0xf
	v_mov_b32_dpp v157, v97 quad_perm:[2,3,0,1] row_mask:0xf bank_mask:0xf
	v_cndmask_b32_e64 v156, v94, v156, s[2:3]
	v_cndmask_b32_e64 v157, v95, v157, s[2:3]
	v_cndmask_b32_e64 v112, v112, v96, s[2:3]
	v_cndmask_b32_e64 v113, v113, v97, s[2:3]
	v_cvt_pk_bf16_f32 v96, v156, v157
	v_cvt_pk_bf16_f32 v97, v112, v113
	global_store_dwordx2 v[86:87], v[96:97], off offset:32
	s_nop 1
	s_and_saveexec_b64 s[0:1], s[44:45]
	s_xor_b64 s[0:1], exec, s[0:1]
	s_cbranch_execz .LBB0_581
	v_cmp_gt_u32_e32 vcc, s59, v178
	v_mov_b64_e32 v[86:87], 0
	s_and_saveexec_b64 s[2:3], vcc
	s_cbranch_execz .LBB0_575
	v_lshlrev_b32_e32 v83, 5, v178
	v_and_b32_e32 v83, 0xfff80, v83
	v_add3_u32 v86, v150, s83, v83
	v_ashrrev_i32_e32 v87, 31, v86
	v_readlane_b32 s4, v254, 14
	v_lshlrev_b64 v[86:87], 9, v[86:87]
	v_readlane_b32 s5, v254, 15
	s_nop 1
	v_lshl_add_u64 v[86:87], s[4:5], 0, v[86:87]
	v_lshl_add_u64 v[86:87], v[172:173], 2, v[86:87]

; __device__ __forceinline__ u32x4 pack8(f32x4 a, f32x4 b) { u32x4 w; w.x = cvtpk(a[0], a[1]); w.y = cvtpk(a[2], a[3]); w.z = cvtpk(b[0], b[1]); w.w = cvtpk(b[2], b[3]); return w; }
;     __device__ __forceinline__ void operator()(const pg8::f32x4 (&acc)[2][2][4][2], const pg8::Unit& u, int wr, int wc, int fr, int fq) const {
;     ...
;                         if (pn == 2 && bj == 1) {
;                             const int vc = cl;
;                             const u32x4 w = pack8(v0, v1);
;                             bf16* vt = VT + ((size_t)((vc >> 6) * (MP / 4) + (row >> 2)) * 64 + (vc & 63)) * 4 + (row & 3);
;                             vt[0] = (bf16)(w.x & 0xffff); vt[4] = (bf16)(w.x >> 16); vt[8] = (bf16)(w.y & 0xffff); vt[12] = (bf16)(w.y >> 16);
;                             vt[16] = (bf16)(w.z & 0xffff); vt[20] = (bf16)(w.z >> 16); vt[24] = (bf16)(w.w & 0xffff); vt[28] = (bf16)(w.w >> 16);
;                             float* dst = nullptr;
;                             if (row < NPT) { const int t = row % LP; if (t >= LP - 128) dst = out + O_WVP + ((size_t)((l * 8 + row / LP) * 128 + (t - (LP - 128)))) * 128 + vc; }
.LBB0_609:
	s_andn2_b64 vcc, exec, s[0:1]
	s_cbranch_vccnz .LBB0_617
	v_ashrrev_i32_e32 v56, 2, v176
	v_add_u32_e32 v56, v56, v88
	v_ashrrev_i32_e32 v57, 31, v56
	v_lshlrev_b64 v[56:57], 9, v[56:57]
	v_lshl_add_u64 v[56:57], s[8:9], 0, v[56:57]
	v_lshl_add_u64 v[56:57], v[56:57], 0, v[80:81]
	v_mov_b32_e32 v83, v81
	v_lshl_add_u64 v[56:57], v[82:83], 2, v[56:57]
	s_waitcnt vmcnt(0)
	s_mov_b32 s0, 0xaaaaaaaa
	s_mov_b32 s1, 0xaaaaaaaa
	s_mov_b32 s2, 0xcccccccc
	s_mov_b32 s3, 0xcccccccc
	s_nop 1
	v_mov_b32_dpp v76, v52 quad_perm:[1,0,3,2] row_mask:0xf bank_mask:0xf
	v_mov_b32_dpp v77, v53 quad_perm:[1,0,3,2] row_mask:0xf bank_mask:0xf
	v_mov_b32_dpp v86, v54 quad_perm:[1,0,3,2] row_mask:0xf bank_mask:0xf
	v_mov_b32_dpp v87, v55 quad_perm:[1,0,3,2] row_mask:0xf bank_mask:0xf
	v_cndmask_b32_e64 v62, v52, v77, s[0:1]
	v_cndmask_b32_e64 v63, v76, v53, s[0:1]
	v_cndmask_b32_e64 v74, v54, v87, s[0:1]
	v_cndmask_b32_e64 v75, v86, v55, s[0:1]
	s_nop 1
	v_mov_b32_dpp v76, v62 quad_perm:[2,3,0,1] row_mask:0xf bank_mask:0xf
	v_mov_b32_dpp v77, v63 quad_perm:[2,3,0,1] row_mask:0xf bank_mask:0xf
	v_mov_b32_dpp v86, v74 quad_perm:[2,3,0,1] row_mask:0xf bank_mask:0xf
	v_mov_b32_dpp v87, v75 quad_perm:[2,3,0,1] row_mask:0xf bank_mask:0xf
	v_cndmask_b32_e64 v86, v62, v86, s[2:3]
	v_cndmask_b32_e64 v87, v63, v87, s[2:3]
	v_cndmask_b32_e64 v76, v76, v74, s[2:3]
	v_cndmask_b32_e64 v77, v77, v75, s[2:3]
	v_cvt_pk_bf16_f32 v62, v86, v87
	v_cvt_pk_bf16_f32 v63, v76, v77
	global_store_dwordx2 v[56:57], v[62:63], off
	s_nop 1
	v_mov_b32_dpp v76, v48 quad_perm:[1,0,3,2] row_mask:0xf bank_mask:0xf
	v_mov_b32_dpp v77, v49 quad_perm:[1,0,3,2] row_mask:0xf bank_mask:0xf
	v_mov_b32_dpp v86, v50 quad_perm:[1,0,3,2] row_mask:0xf bank_mask:0xf
	v_mov_b32_dpp v87, v51 quad_perm:[1,0,3,2] row_mask:0xf bank_mask:0xf
	v_cndmask_b32_e64 v62, v48, v77, s[0:1]
	v_cndmask_b32_e64 v63, v76, v49, s[0:1]
	v_cndmask_b32_e64 v74, v50, v87, s[0:1]
	v_cndmask_b32_e64 v75, v86, v51, s[0:1]
	s_nop 1
	v_mov_b32_dpp v76, v62 quad_perm:[2,3,0,1] row_mask:0xf bank_mask:0xf
	v_mov_b32_dpp v77, v63 quad_perm:[2,3,0,1] row_mask:0xf bank_mask:0xf
	v_mov_b32_dpp v86, v74 quad_perm:[2,3,0,1] row_mask:0xf bank_mask:0xf
	v_mov_b32_dpp v87, v75 quad_perm:[2,3,0,1] row_mask:0xf bank_mask:0xf
	v_cndmask_b32_e64 v86, v62, v86, s[2:3]
	v_cndmask_b32_e64 v87, v63, v87, s[2:3]
	v_cndmask_b32_e64 v76, v76, v74, s[2:3]
	v_cndmask_b32_e64 v77, v77, v75, s[2:3]
	v_cvt_pk_bf16_f32 v74, v86, v87
	v_cvt_pk_bf16_f32 v75, v76, v77
	global_store_dwordx2 v[56:57], v[74:75], off offset:32
	s_nop 1
	s_and_saveexec_b64 s[0:1], s[42:43]
	s_xor_b64 s[0:1], exec, s[0:1]
	s_cbranch_execz .LBB0_627
	v_cmp_gt_u32_e32 vcc, s59, v176
	v_mov_b64_e32 v[56:57], 0
	s_and_saveexec_b64 s[2:3], vcc
	s_cbranch_execz .LBB0_613
	v_lshlrev_b32_e32 v56, 5, v176
	v_and_b32_e32 v56, 0xfff80, v56
	v_add3_u32 v56, v150, s83, v56
	v_ashrrev_i32_e32 v57, 31, v56
	v_readlane_b32 s4, v254, 14
	v_lshlrev_b64 v[56:57], 9, v[56:57]
	v_readlane_b32 s5, v254, 15
	s_nop 1
	v_lshl_add_u64 v[56:57], s[4:5], 0, v[56:57]
	v_lshl_add_u64 v[56:57], v[172:173], 2, v[56:57]

; __device__ __forceinline__ u32x4 pack8(f32x4 a, f32x4 b) { u32x4 w; w.x = cvtpk(a[0], a[1]); w.y = cvtpk(a[2], a[3]); w.z = cvtpk(b[0], b[1]); w.w = cvtpk(b[2], b[3]); return w; }
;     __device__ __forceinline__ void operator()(const pg8::f32x4 (&acc)[2][2][4][2], const pg8::Unit& u, int wr, int wc, int fr, int fq) const {
;     ...
;                         if (pn == 2 && bj == 1) {
;                             const int vc = cl;
;                             const u32x4 w = pack8(v0, v1);
;                             bf16* vt = VT + ((size_t)((vc >> 6) * (MP / 4) + (row >> 2)) * 64 + (vc & 63)) * 4 + (row & 3);
;                             vt[0] = (bf16)(w.x & 0xffff); vt[4] = (bf16)(w.x >> 16); vt[8] = (bf16)(w.y & 0xffff); vt[12] = (bf16)(w.y >> 16);
;                             vt[16] = (bf16)(w.z & 0xffff); vt[20] = (bf16)(w.z >> 16); vt[24] = (bf16)(w.w & 0xffff); vt[28] = (bf16)(w.w >> 16);
;                             float* dst = nullptr;
;                             if (row < NPT) { const int t = row % LP; if (t >= LP - 128) dst = out + O_WVP + ((size_t)((l * 8 + row / LP) * 128 + (t - (LP - 128)))) * 128 + vc; }
.LBB0_658:
	s_waitcnt vmcnt(2)
	v_ashrrev_i32_e32 v56, 2, v136
	v_add_u32_e32 v56, v56, v88
	v_ashrrev_i32_e32 v57, 31, v56
	v_lshlrev_b64 v[56:57], 9, v[56:57]
	v_lshl_add_u64 v[56:57], s[8:9], 0, v[56:57]
	v_lshl_add_u64 v[56:57], v[56:57], 0, v[80:81]
	v_mov_b32_e32 v83, v81
	v_lshl_add_u64 v[56:57], v[82:83], 2, v[56:57]
	s_waitcnt vmcnt(0)
	s_mov_b32 s0, 0xaaaaaaaa
	s_mov_b32 s1, 0xaaaaaaaa
	s_mov_b32 s2, 0xcccccccc
	s_mov_b32 s3, 0xcccccccc
	s_nop 1
	v_mov_b32_dpp v72, v44 quad_perm:[1,0,3,2] row_mask:0xf bank_mask:0xf
	v_mov_b32_dpp v73, v45 quad_perm:[1,0,3,2] row_mask:0xf bank_mask:0xf
	v_mov_b32_dpp v74, v46 quad_perm:[1,0,3,2] row_mask:0xf bank_mask:0xf
	v_mov_b32_dpp v75, v47 quad_perm:[1,0,3,2] row_mask:0xf bank_mask:0xf
	v_cndmask_b32_e64 v62, v44, v73, s[0:1]
	v_cndmask_b32_e64 v63, v72, v45, s[0:1]
	v_cndmask_b32_e64 v70, v46, v75, s[0:1]
	v_cndmask_b32_e64 v71, v74, v47, s[0:1]
	s_nop 1
	v_mov_b32_dpp v72, v62 quad_perm:[2,3,0,1] row_mask:0xf bank_mask:0xf
	v_mov_b32_dpp v73, v63 quad_perm:[2,3,0,1] row_mask:0xf bank_mask:0xf
	v_mov_b32_dpp v74, v70 quad_perm:[2,3,0,1] row_mask:0xf bank_mask:0xf
	v_mov_b32_dpp v75, v71 quad_perm:[2,3,0,1] row_mask:0xf bank_mask:0xf
	v_cndmask_b32_e64 v74, v62, v74, s[2:3]
	v_cndmask_b32_e64 v75, v63, v75, s[2:3]
	v_cndmask_b32_e64 v72, v72, v70, s[2:3]
	v_cndmask_b32_e64 v73, v73, v71, s[2:3]
	v_cvt_pk_bf16_f32 v62, v74, v75
	v_cvt_pk_bf16_f32 v63, v72, v73
	global_store_dwordx2 v[56:57], v[62:63], off
	s_nop 1
	v_mov_b32_dpp v72, v40 quad_perm:[1,0,3,2] row_mask:0xf bank_mask:0xf
	v_mov_b32_dpp v73, v41 quad_perm:[1,0,3,2] row_mask:0xf bank_mask:0xf
	v_mov_b32_dpp v74, v42 quad_perm:[1,0,3,2] row_mask:0xf bank_mask:0xf
	v_mov_b32_dpp v75, v43 quad_perm:[1,0,3,2] row_mask:0xf bank_mask:0xf
	v_cndmask_b32_e64 v62, v40, v73, s[0:1]
	v_cndmask_b32_e64 v63, v72, v41, s[0:1]
	v_cndmask_b32_e64 v70, v42, v75, s[0:1]
	v_cndmask_b32_e64 v71, v74, v43, s[0:1]
	s_nop 1
	v_mov_b32_dpp v72, v62 quad_perm:[2,3,0,1] row_mask:0xf bank_mask:0xf
	v_mov_b32_dpp v73, v63 quad_perm:[2,3,0,1] row_mask:0xf bank_mask:0xf
	v_mov_b32_dpp v74, v70 quad_perm:[2,3,0,1] row_mask:0xf bank_mask:0xf
	v_mov_b32_dpp v75, v71 quad_perm:[2,3,0,1] row_mask:0xf bank_mask:0xf
	v_cndmask_b32_e64 v74, v62, v74, s[2:3]
	v_cndmask_b32_e64 v75, v63, v75, s[2:3]
	v_cndmask_b32_e64 v72, v72, v70, s[2:3]
	v_cndmask_b32_e64 v73, v73, v71, s[2:3]
	v_cvt_pk_bf16_f32 v70, v74, v75
	v_cvt_pk_bf16_f32 v71, v72, v73
	global_store_dwordx2 v[56:57], v[70:71], off offset:32
	s_nop 1
	s_and_saveexec_b64 s[0:1], s[46:47]
	s_xor_b64 s[0:1], exec, s[0:1]
	s_cbranch_execz .LBB0_686
	v_cmp_gt_u32_e32 vcc, s59, v136
	v_mov_b64_e32 v[56:57], 0
	s_and_saveexec_b64 s[2:3], vcc
	s_cbranch_execz .LBB0_661
	v_lshlrev_b32_e32 v56, 5, v136
	v_and_b32_e32 v56, 0xfff80, v56
	v_add3_u32 v56, v150, s83, v56
	v_ashrrev_i32_e32 v57, 31, v56
	v_readlane_b32 s4, v254, 14
	v_lshlrev_b64 v[56:57], 9, v[56:57]
	v_readlane_b32 s5, v254, 15
	s_nop 1
	v_lshl_add_u64 v[56:57], s[4:5], 0, v[56:57]
	v_lshl_add_u64 v[56:57], v[172:173], 2, v[56:57]

; __device__ __forceinline__ u32x4 pack8(f32x4 a, f32x4 b) { u32x4 w; w.x = cvtpk(a[0], a[1]); w.y = cvtpk(a[2], a[3]); w.z = cvtpk(b[0], b[1]); w.w = cvtpk(b[2], b[3]); return w; }
;     __device__ __forceinline__ void operator()(const pg8::f32x4 (&acc)[2][2][4][2], const pg8::Unit& u, int wr, int wc, int fr, int fq) const {
;     ...
;                         if (pn == 2 && bj == 1) {
;                             const int vc = cl;
;                             const u32x4 w = pack8(v0, v1);
;                             bf16* vt = VT + ((size_t)((vc >> 6) * (MP / 4) + (row >> 2)) * 64 + (vc & 63)) * 4 + (row & 3);
;                             vt[0] = (bf16)(w.x & 0xffff); vt[4] = (bf16)(w.x >> 16); vt[8] = (bf16)(w.y & 0xffff); vt[12] = (bf16)(w.y >> 16);
;                             vt[16] = (bf16)(w.z & 0xffff); vt[20] = (bf16)(w.z >> 16); vt[24] = (bf16)(w.w & 0xffff); vt[28] = (bf16)(w.w >> 16);
;                             float* dst = nullptr;
;                             if (row < NPT) { const int t = row % LP; if (t >= LP - 128) dst = out + O_WVP + ((size_t)((l * 8 + row / LP) * 128 + (t - (LP - 128)))) * 128 + vc; }
.LBB0_668:
	s_andn2_b64 vcc, exec, s[0:1]
	s_cbranch_vccnz .LBB0_676
	v_ashrrev_i32_e32 v40, 2, v122
	v_add_u32_e32 v40, v40, v88
	v_ashrrev_i32_e32 v41, 31, v40
	v_lshlrev_b64 v[40:41], 9, v[40:41]
	v_lshl_add_u64 v[40:41], s[8:9], 0, v[40:41]
	v_lshl_add_u64 v[40:41], v[40:41], 0, v[80:81]
	v_mov_b32_e32 v83, v81
	v_lshl_add_u64 v[40:41], v[82:83], 2, v[40:41]
	v_cmp_lt_i32_e32 vcc, s58, v122
	s_waitcnt vmcnt(0)
	s_mov_b32 s0, 0xaaaaaaaa
	s_mov_b32 s1, 0xaaaaaaaa
	s_mov_b32 s2, 0xcccccccc
	s_mov_b32 s3, 0xcccccccc
	s_nop 1
	v_mov_b32_dpp v54, v36 quad_perm:[1,0,3,2] row_mask:0xf bank_mask:0xf
	v_mov_b32_dpp v55, v37 quad_perm:[1,0,3,2] row_mask:0xf bank_mask:0xf
	v_mov_b32_dpp v56, v38 quad_perm:[1,0,3,2] row_mask:0xf bank_mask:0xf
	v_mov_b32_dpp v57, v39 quad_perm:[1,0,3,2] row_mask:0xf bank_mask:0xf
	v_cndmask_b32_e64 v46, v36, v55, s[0:1]
	v_cndmask_b32_e64 v47, v54, v37, s[0:1]
	v_cndmask_b32_e64 v52, v38, v57, s[0:1]
	v_cndmask_b32_e64 v53, v56, v39, s[0:1]
	s_nop 1
	v_mov_b32_dpp v54, v46 quad_perm:[2,3,0,1] row_mask:0xf bank_mask:0xf
	v_mov_b32_dpp v55, v47 quad_perm:[2,3,0,1] row_mask:0xf bank_mask:0xf
	v_mov_b32_dpp v56, v52 quad_perm:[2,3,0,1] row_mask:0xf bank_mask:0xf
	v_mov_b32_dpp v57, v53 quad_perm:[2,3,0,1] row_mask:0xf bank_mask:0xf
	v_cndmask_b32_e64 v56, v46, v56, s[2:3]
	v_cndmask_b32_e64 v57, v47, v57, s[2:3]
	v_cndmask_b32_e64 v54, v54, v52, s[2:3]
	v_cndmask_b32_e64 v55, v55, v53, s[2:3]
	v_cvt_pk_bf16_f32 v46, v56, v57
	v_cvt_pk_bf16_f32 v47, v54, v55
	global_store_dwordx2 v[40:41], v[46:47], off
	s_nop 1
	v_mov_b32_dpp v54, v32 quad_perm:[1,0,3,2] row_mask:0xf bank_mask:0xf
	v_mov_b32_dpp v55, v33 quad_perm:[1,0,3,2] row_mask:0xf bank_mask:0xf
	v_mov_b32_dpp v56, v34 quad_perm:[1,0,3,2] row_mask:0xf bank_mask:0xf
	v_mov_b32_dpp v57, v35 quad_perm:[1,0,3,2] row_mask:0xf bank_mask:0xf
	v_cndmask_b32_e64 v46, v32, v55, s[0:1]
	v_cndmask_b32_e64 v47, v54, v33, s[0:1]
	v_cndmask_b32_e64 v52, v34, v57, s[0:1]
	v_cndmask_b32_e64 v53, v56, v35, s[0:1]
	s_nop 1
	v_mov_b32_dpp v54, v46 quad_perm:[2,3,0,1] row_mask:0xf bank_mask:0xf
	v_mov_b32_dpp v55, v47 quad_perm:[2,3,0,1] row_mask:0xf bank_mask:0xf
	v_mov_b32_dpp v56, v52 quad_perm:[2,3,0,1] row_mask:0xf bank_mask:0xf
	v_mov_b32_dpp v57, v53 quad_perm:[2,3,0,1] row_mask:0xf bank_mask:0xf
	v_cndmask_b32_e64 v56, v46, v56, s[2:3]
	v_cndmask_b32_e64 v57, v47, v57, s[2:3]
	v_cndmask_b32_e64 v54, v54, v52, s[2:3]
	v_cndmask_b32_e64 v55, v55, v53, s[2:3]
	v_cvt_pk_bf16_f32 v52, v56, v57
	v_cvt_pk_bf16_f32 v53, v54, v55
	global_store_dwordx2 v[40:41], v[52:53], off offset:32
	s_nop 1
	s_and_saveexec_b64 s[0:1], vcc
	s_xor_b64 s[0:1], exec, s[0:1]
	s_cbranch_execz .LBB0_690
	v_cmp_gt_u32_e32 vcc, s59, v122
	v_mov_b64_e32 v[40:41], 0
	s_and_saveexec_b64 s[2:3], vcc
	s_cbranch_execz .LBB0_672
	v_lshlrev_b32_e32 v40, 5, v122
	v_and_b32_e32 v40, 0xfff80, v40
	v_add3_u32 v40, v150, s83, v40
	v_ashrrev_i32_e32 v41, 31, v40
	v_readlane_b32 s4, v254, 14
	v_lshlrev_b64 v[40:41], 9, v[40:41]
	v_readlane_b32 s5, v254, 15
	s_nop 1
	v_lshl_add_u64 v[40:41], s[4:5], 0, v[40:41]
	v_lshl_add_u64 v[40:41], v[172:173], 2, v[40:41]

; __device__ __forceinline__ u32x4 pack8(f32x4 a, f32x4 b) { u32x4 w; w.x = cvtpk(a[0], a[1]); w.y = cvtpk(a[2], a[3]); w.z = cvtpk(b[0], b[1]); w.w = cvtpk(b[2], b[3]); return w; }
;     __device__ __forceinline__ void operator()(const pg8::f32x4 (&acc)[2][2][4][2], const pg8::Unit& u, int wr, int wc, int fr, int fq) const {
;     ...
;                         if (pn == 2 && bj == 1) {
;                             const int vc = cl;
;                             const u32x4 w = pack8(v0, v1);
;                             bf16* vt = VT + ((size_t)((vc >> 6) * (MP / 4) + (row >> 2)) * 64 + (vc & 63)) * 4 + (row & 3);
;                             vt[0] = (bf16)(w.x & 0xffff); vt[4] = (bf16)(w.x >> 16); vt[8] = (bf16)(w.y & 0xffff); vt[12] = (bf16)(w.y >> 16);
;                             vt[16] = (bf16)(w.z & 0xffff); vt[20] = (bf16)(w.z >> 16); vt[24] = (bf16)(w.w & 0xffff); vt[28] = (bf16)(w.w >> 16);
;                             float* dst = nullptr;
;                             if (row < NPT) { const int t = row % LP; if (t >= LP - 128) dst = out + O_WVP + ((size_t)((l * 8 + row / LP) * 128 + (t - (LP - 128)))) * 128 + vc; }
.LBB0_721:
	s_waitcnt vmcnt(2)
	v_ashrrev_i32_e32 v40, 2, v114
	v_add_u32_e32 v40, v40, v88
	v_ashrrev_i32_e32 v41, 31, v40
	v_lshlrev_b64 v[40:41], 9, v[40:41]
	v_lshl_add_u64 v[40:41], s[8:9], 0, v[40:41]
	v_lshl_add_u64 v[40:41], v[40:41], 0, v[80:81]
	v_mov_b32_e32 v83, v81
	v_lshl_add_u64 v[40:41], v[82:83], 2, v[40:41]
	s_waitcnt vmcnt(0)
	s_mov_b32 s0, 0xaaaaaaaa
	s_mov_b32 s1, 0xaaaaaaaa
	s_mov_b32 s2, 0xcccccccc
	s_mov_b32 s3, 0xcccccccc
	s_nop 1
	v_mov_b32_dpp v52, v28 quad_perm:[1,0,3,2] row_mask:0xf bank_mask:0xf
	v_mov_b32_dpp v53, v29 quad_perm:[1,0,3,2] row_mask:0xf bank_mask:0xf
	v_mov_b32_dpp v54, v30 quad_perm:[1,0,3,2] row_mask:0xf bank_mask:0xf
	v_mov_b32_dpp v55, v31 quad_perm:[1,0,3,2] row_mask:0xf bank_mask:0xf
	v_cndmask_b32_e64 v48, v28, v53, s[0:1]
	v_cndmask_b32_e64 v49, v52, v29, s[0:1]
	v_cndmask_b32_e64 v50, v30, v55, s[0:1]
	v_cndmask_b32_e64 v51, v54, v31, s[0:1]
	s_nop 1
	v_mov_b32_dpp v52, v48 quad_perm:[2,3,0,1] row_mask:0xf bank_mask:0xf
	v_mov_b32_dpp v53, v49 quad_perm:[2,3,0,1] row_mask:0xf bank_mask:0xf
	v_mov_b32_dpp v54, v50 quad_perm:[2,3,0,1] row_mask:0xf bank_mask:0xf
	v_mov_b32_dpp v55, v51 quad_perm:[2,3,0,1] row_mask:0xf bank_mask:0xf
	v_cndmask_b32_e64 v54, v48, v54, s[2:3]
	v_cndmask_b32_e64 v55, v49, v55, s[2:3]
	v_cndmask_b32_e64 v52, v52, v50, s[2:3]
	v_cndmask_b32_e64 v53, v53, v51, s[2:3]
	v_cvt_pk_bf16_f32 v48, v54, v55
	v_cvt_pk_bf16_f32 v49, v52, v53
	global_store_dwordx2 v[40:41], v[48:49], off
	s_nop 1
	v_mov_b32_dpp v52, v24 quad_perm:[1,0,3,2] row_mask:0xf bank_mask:0xf
	v_mov_b32_dpp v53, v25 quad_perm:[1,0,3,2] row_mask:0xf bank_mask:0xf
	v_mov_b32_dpp v54, v26 quad_perm:[1,0,3,2] row_mask:0xf bank_mask:0xf
	v_mov_b32_dpp v55, v27 quad_perm:[1,0,3,2] row_mask:0xf bank_mask:0xf
	v_cndmask_b32_e64 v48, v24, v53, s[0:1]
	v_cndmask_b32_e64 v49, v52, v25, s[0:1]
	v_cndmask_b32_e64 v50, v26, v55, s[0:1]
	v_cndmask_b32_e64 v51, v54, v27, s[0:1]
	s_nop 1
	v_mov_b32_dpp v52, v48 quad_perm:[2,3,0,1] row_mask:0xf bank_mask:0xf
	v_mov_b32_dpp v53, v49 quad_perm:[2,3,0,1] row_mask:0xf bank_mask:0xf
	v_mov_b32_dpp v54, v50 quad_perm:[2,3,0,1] row_mask:0xf bank_mask:0xf
	v_mov_b32_dpp v55, v51 quad_perm:[2,3,0,1] row_mask:0xf bank_mask:0xf
	v_cndmask_b32_e64 v54, v48, v54, s[2:3]
	v_cndmask_b32_e64 v55, v49, v55, s[2:3]
	v_cndmask_b32_e64 v52, v52, v50, s[2:3]
	v_cndmask_b32_e64 v53, v53, v51, s[2:3]
	v_cvt_pk_bf16_f32 v50, v54, v55
	v_cvt_pk_bf16_f32 v51, v52, v53
	global_store_dwordx2 v[40:41], v[50:51], off offset:32
	s_nop 1
	s_and_saveexec_b64 s[0:1], s[48:49]
	s_xor_b64 s[0:1], exec, s[0:1]
	s_cbranch_execz .LBB0_749
	v_cmp_gt_u32_e32 vcc, s59, v114
	v_mov_b64_e32 v[40:41], 0
	s_and_saveexec_b64 s[2:3], vcc
	s_cbranch_execz .LBB0_724
	v_lshlrev_b32_e32 v40, 5, v114
	v_and_b32_e32 v40, 0xfff80, v40
	v_add3_u32 v40, v150, s83, v40
	v_ashrrev_i32_e32 v41, 31, v40
	v_readlane_b32 s4, v254, 14
	v_lshlrev_b64 v[40:41], 9, v[40:41]
	v_readlane_b32 s5, v254, 15
	s_nop 1
	v_lshl_add_u64 v[40:41], s[4:5], 0, v[40:41]
	v_lshl_add_u64 v[40:41], v[172:173], 2, v[40:41]

; __device__ __forceinline__ u32x4 pack8(f32x4 a, f32x4 b) { u32x4 w; w.x = cvtpk(a[0], a[1]); w.y = cvtpk(a[2], a[3]); w.z = cvtpk(b[0], b[1]); w.w = cvtpk(b[2], b[3]); return w; }
;     __device__ __forceinline__ void operator()(const pg8::f32x4 (&acc)[2][2][4][2], const pg8::Unit& u, int wr, int wc, int fr, int fq) const {
;     ...
;                         if (pn == 2 && bj == 1) {
;                             const int vc = cl;
;                             const u32x4 w = pack8(v0, v1);
;                             bf16* vt = VT + ((size_t)((vc >> 6) * (MP / 4) + (row >> 2)) * 64 + (vc & 63)) * 4 + (row & 3);
;                             vt[0] = (bf16)(w.x & 0xffff); vt[4] = (bf16)(w.x >> 16); vt[8] = (bf16)(w.y & 0xffff); vt[12] = (bf16)(w.y >> 16);
;                             vt[16] = (bf16)(w.z & 0xffff); vt[20] = (bf16)(w.z >> 16); vt[24] = (bf16)(w.w & 0xffff); vt[28] = (bf16)(w.w >> 16);
;                             float* dst = nullptr;
;                             if (row < NPT) { const int t = row % LP; if (t >= LP - 128) dst = out + O_WVP + ((size_t)((l * 8 + row / LP) * 128 + (t - (LP - 128)))) * 128 + vc; }
.LBB0_731:
	s_andn2_b64 vcc, exec, s[0:1]
	s_cbranch_vccnz .LBB0_739
	v_ashrrev_i32_e32 v24, 2, v106
	v_add_u32_e32 v24, v24, v88
	v_ashrrev_i32_e32 v25, 31, v24
	v_lshlrev_b64 v[24:25], 9, v[24:25]
	v_lshl_add_u64 v[24:25], s[8:9], 0, v[24:25]
	v_lshl_add_u64 v[24:25], v[24:25], 0, v[80:81]
	v_mov_b32_e32 v83, v81
	v_lshl_add_u64 v[24:25], v[82:83], 2, v[24:25]
	v_cmp_lt_i32_e32 vcc, s58, v106
	s_waitcnt vmcnt(0)
	s_mov_b32 s0, 0xaaaaaaaa
	s_mov_b32 s1, 0xaaaaaaaa
	s_mov_b32 s2, 0xcccccccc
	s_mov_b32 s3, 0xcccccccc
	s_nop 1
	v_mov_b32_dpp v38, v20 quad_perm:[1,0,3,2] row_mask:0xf bank_mask:0xf
	v_mov_b32_dpp v39, v21 quad_perm:[1,0,3,2] row_mask:0xf bank_mask:0xf
	v_mov_b32_dpp v48, v22 quad_perm:[1,0,3,2] row_mask:0xf bank_mask:0xf
	v_mov_b32_dpp v49, v23 quad_perm:[1,0,3,2] row_mask:0xf bank_mask:0xf
	v_cndmask_b32_e64 v30, v20, v39, s[0:1]
	v_cndmask_b32_e64 v31, v38, v21, s[0:1]
	v_cndmask_b32_e64 v36, v22, v49, s[0:1]
	v_cndmask_b32_e64 v37, v48, v23, s[0:1]
	s_nop 1
	v_mov_b32_dpp v38, v30 quad_perm:[2,3,0,1] row_mask:0xf bank_mask:0xf
	v_mov_b32_dpp v39, v31 quad_perm:[2,3,0,1] row_mask:0xf bank_mask:0xf
	v_mov_b32_dpp v48, v36 quad_perm:[2,3,0,1] row_mask:0xf bank_mask:0xf
	v_mov_b32_dpp v49, v37 quad_perm:[2,3,0,1] row_mask:0xf bank_mask:0xf
	v_cndmask_b32_e64 v48, v30, v48, s[2:3]
	v_cndmask_b32_e64 v49, v31, v49, s[2:3]
	v_cndmask_b32_e64 v38, v38, v36, s[2:3]
	v_cndmask_b32_e64 v39, v39, v37, s[2:3]
	v_cvt_pk_bf16_f32 v30, v48, v49
	v_cvt_pk_bf16_f32 v31, v38, v39
	global_store_dwordx2 v[24:25], v[30:31], off
	s_nop 1
	v_mov_b32_dpp v38, v16 quad_perm:[1,0,3,2] row_mask:0xf bank_mask:0xf
	v_mov_b32_dpp v39, v17 quad_perm:[1,0,3,2] row_mask:0xf bank_mask:0xf
	v_mov_b32_dpp v48, v18 quad_perm:[1,0,3,2] row_mask:0xf bank_mask:0xf
	v_mov_b32_dpp v49, v19 quad_perm:[1,0,3,2] row_mask:0xf bank_mask:0xf
	v_cndmask_b32_e64 v30, v16, v39, s[0:1]
	v_cndmask_b32_e64 v31, v38, v17, s[0:1]
	v_cndmask_b32_e64 v36, v18, v49, s[0:1]
	v_cndmask_b32_e64 v37, v48, v19, s[0:1]
	s_nop 1
	v_mov_b32_dpp v38, v30 quad_perm:[2,3,0,1] row_mask:0xf bank_mask:0xf
	v_mov_b32_dpp v39, v31 quad_perm:[2,3,0,1] row_mask:0xf bank_mask:0xf
	v_mov_b32_dpp v48, v36 quad_perm:[2,3,0,1] row_mask:0xf bank_mask:0xf
	v_mov_b32_dpp v49, v37 quad_perm:[2,3,0,1] row_mask:0xf bank_mask:0xf
	v_cndmask_b32_e64 v48, v30, v48, s[2:3]
	v_cndmask_b32_e64 v49, v31, v49, s[2:3]
	v_cndmask_b32_e64 v38, v38, v36, s[2:3]
	v_cndmask_b32_e64 v39, v39, v37, s[2:3]
	v_cvt_pk_bf16_f32 v36, v48, v49
	v_cvt_pk_bf16_f32 v37, v38, v39
	global_store_dwordx2 v[24:25], v[36:37], off offset:32
	s_nop 1
	s_and_saveexec_b64 s[0:1], vcc
	s_xor_b64 s[0:1], exec, s[0:1]
	s_cbranch_execz .LBB0_753
	v_cmp_gt_u32_e32 vcc, s59, v106
	v_mov_b64_e32 v[24:25], 0
	s_and_saveexec_b64 s[2:3], vcc
	s_cbranch_execz .LBB0_735
	v_lshlrev_b32_e32 v24, 5, v106
	v_and_b32_e32 v24, 0xfff80, v24
	v_add3_u32 v24, v150, s83, v24
	v_ashrrev_i32_e32 v25, 31, v24
	v_readlane_b32 s4, v254, 14
	v_lshlrev_b64 v[24:25], 9, v[24:25]
	v_readlane_b32 s5, v254, 15
	s_nop 1
	v_lshl_add_u64 v[24:25], s[4:5], 0, v[24:25]
	v_lshl_add_u64 v[24:25], v[172:173], 2, v[24:25]

; __device__ __forceinline__ u32x4 pack8(f32x4 a, f32x4 b) { u32x4 w; w.x = cvtpk(a[0], a[1]); w.y = cvtpk(a[2], a[3]); w.z = cvtpk(b[0], b[1]); w.w = cvtpk(b[2], b[3]); return w; }
;     __device__ __forceinline__ void operator()(const pg8::f32x4 (&acc)[2][2][4][2], const pg8::Unit& u, int wr, int wc, int fr, int fq) const {
;     ...
;                         if (pn == 2 && bj == 1) {
;                             const int vc = cl;
;                             const u32x4 w = pack8(v0, v1);
;                             bf16* vt = VT + ((size_t)((vc >> 6) * (MP / 4) + (row >> 2)) * 64 + (vc & 63)) * 4 + (row & 3);
;                             vt[0] = (bf16)(w.x & 0xffff); vt[4] = (bf16)(w.x >> 16); vt[8] = (bf16)(w.y & 0xffff); vt[12] = (bf16)(w.y >> 16);
;                             vt[16] = (bf16)(w.z & 0xffff); vt[20] = (bf16)(w.z >> 16); vt[24] = (bf16)(w.w & 0xffff); vt[28] = (bf16)(w.w >> 16);
;                             float* dst = nullptr;
;                             if (row < NPT) { const int t = row % LP; if (t >= LP - 128) dst = out + O_WVP + ((size_t)((l * 8 + row / LP) * 128 + (t - (LP - 128)))) * 128 + vc; }
.LBB0_784:
	s_waitcnt vmcnt(2)
	v_ashrrev_i32_e32 v24, 2, v98
	v_add_u32_e32 v24, v24, v88
	v_ashrrev_i32_e32 v25, 31, v24
	v_lshlrev_b64 v[24:25], 9, v[24:25]
	v_lshl_add_u64 v[24:25], s[8:9], 0, v[24:25]
	v_lshl_add_u64 v[24:25], v[24:25], 0, v[80:81]
	v_mov_b32_e32 v83, v81
	v_lshl_add_u64 v[24:25], v[82:83], 2, v[24:25]
	s_waitcnt vmcnt(0)
	s_mov_b32 s0, 0xaaaaaaaa
	s_mov_b32 s1, 0xaaaaaaaa
	s_mov_b32 s2, 0xcccccccc
	s_mov_b32 s3, 0xcccccccc
	s_nop 1
	v_mov_b32_dpp v34, v12 quad_perm:[1,0,3,2] row_mask:0xf bank_mask:0xf
	v_mov_b32_dpp v35, v13 quad_perm:[1,0,3,2] row_mask:0xf bank_mask:0xf
	v_mov_b32_dpp v36, v14 quad_perm:[1,0,3,2] row_mask:0xf bank_mask:0xf
	v_mov_b32_dpp v37, v15 quad_perm:[1,0,3,2] row_mask:0xf bank_mask:0xf
	v_cndmask_b32_e64 v30, v12, v35, s[0:1]
	v_cndmask_b32_e64 v31, v34, v13, s[0:1]
	v_cndmask_b32_e64 v32, v14, v37, s[0:1]
	v_cndmask_b32_e64 v33, v36, v15, s[0:1]
	s_nop 1
	v_mov_b32_dpp v34, v30 quad_perm:[2,3,0,1] row_mask:0xf bank_mask:0xf
	v_mov_b32_dpp v35, v31 quad_perm:[2,3,0,1] row_mask:0xf bank_mask:0xf
	v_mov_b32_dpp v36, v32 quad_perm:[2,3,0,1] row_mask:0xf bank_mask:0xf
	v_mov_b32_dpp v37, v33 quad_perm:[2,3,0,1] row_mask:0xf bank_mask:0xf
	v_cndmask_b32_e64 v36, v30, v36, s[2:3]
	v_cndmask_b32_e64 v37, v31, v37, s[2:3]
	v_cndmask_b32_e64 v34, v34, v32, s[2:3]
	v_cndmask_b32_e64 v35, v35, v33, s[2:3]
	v_cvt_pk_bf16_f32 v30, v36, v37
	v_cvt_pk_bf16_f32 v31, v34, v35
	global_store_dwordx2 v[24:25], v[30:31], off
	s_nop 1
	v_mov_b32_dpp v34, v8 quad_perm:[1,0,3,2] row_mask:0xf bank_mask:0xf
	v_mov_b32_dpp v35, v9 quad_perm:[1,0,3,2] row_mask:0xf bank_mask:0xf
	v_mov_b32_dpp v36, v10 quad_perm:[1,0,3,2] row_mask:0xf bank_mask:0xf
	v_mov_b32_dpp v37, v11 quad_perm:[1,0,3,2] row_mask:0xf bank_mask:0xf
	v_cndmask_b32_e64 v30, v8, v35, s[0:1]
	v_cndmask_b32_e64 v31, v34, v9, s[0:1]
	v_cndmask_b32_e64 v32, v10, v37, s[0:1]
	v_cndmask_b32_e64 v33, v36, v11, s[0:1]
	s_nop 1
	v_mov_b32_dpp v34, v30 quad_perm:[2,3,0,1] row_mask:0xf bank_mask:0xf
	v_mov_b32_dpp v35, v31 quad_perm:[2,3,0,1] row_mask:0xf bank_mask:0xf
	v_mov_b32_dpp v36, v32 quad_perm:[2,3,0,1] row_mask:0xf bank_mask:0xf
	v_mov_b32_dpp v37, v33 quad_perm:[2,3,0,1] row_mask:0xf bank_mask:0xf
	v_cndmask_b32_e64 v36, v30, v36, s[2:3]
	v_cndmask_b32_e64 v37, v31, v37, s[2:3]
	v_cndmask_b32_e64 v34, v34, v32, s[2:3]
	v_cndmask_b32_e64 v35, v35, v33, s[2:3]
	v_cvt_pk_bf16_f32 v32, v36, v37
	v_cvt_pk_bf16_f32 v33, v34, v35
	global_store_dwordx2 v[24:25], v[32:33], off offset:32
	s_nop 1
	s_and_saveexec_b64 s[0:1], s[50:51]
	s_xor_b64 s[0:1], exec, s[0:1]
	s_cbranch_execz .LBB0_803
	v_cmp_gt_u32_e32 vcc, s59, v98
	v_mov_b64_e32 v[24:25], 0
	s_and_saveexec_b64 s[2:3], vcc
	s_cbranch_execz .LBB0_787
	v_lshlrev_b32_e32 v24, 5, v98
	v_and_b32_e32 v24, 0xfff80, v24
	v_add3_u32 v24, v150, s83, v24
	v_ashrrev_i32_e32 v25, 31, v24
	v_readlane_b32 s4, v254, 14
	v_lshlrev_b64 v[24:25], 9, v[24:25]
	v_readlane_b32 s5, v254, 15
	s_nop 1
	v_lshl_add_u64 v[24:25], s[4:5], 0, v[24:25]
	v_lshl_add_u64 v[24:25], v[172:173], 2, v[24:25]

; __device__ __forceinline__ u32x4 pack8(f32x4 a, f32x4 b) { u32x4 w; w.x = cvtpk(a[0], a[1]); w.y = cvtpk(a[2], a[3]); w.z = cvtpk(b[0], b[1]); w.w = cvtpk(b[2], b[3]); return w; }
;     __device__ __forceinline__ void operator()(const pg8::f32x4 (&acc)[2][2][4][2], const pg8::Unit& u, int wr, int wc, int fr, int fq) const {
;     ...
;                         if (pn == 2 && bj == 1) {
;                             const int vc = cl;
;                             const u32x4 w = pack8(v0, v1);
;                             bf16* vt = VT + ((size_t)((vc >> 6) * (MP / 4) + (row >> 2)) * 64 + (vc & 63)) * 4 + (row & 3);
;                             vt[0] = (bf16)(w.x & 0xffff); vt[4] = (bf16)(w.x >> 16); vt[8] = (bf16)(w.y & 0xffff); vt[12] = (bf16)(w.y >> 16);
;                             vt[16] = (bf16)(w.z & 0xffff); vt[20] = (bf16)(w.z >> 16); vt[24] = (bf16)(w.w & 0xffff); vt[28] = (bf16)(w.w >> 16);
;                             float* dst = nullptr;
;                             if (row < NPT) { const int t = row % LP; if (t >= LP - 128) dst = out + O_WVP + ((size_t)((l * 8 + row / LP) * 128 + (t - (LP - 128)))) * 128 + vc; }
.LBB0_794:
	s_andn2_b64 vcc, exec, s[0:1]
	s_cbranch_vccnz .LBB0_802
	v_ashrrev_i32_e32 v8, 2, v78
	v_add_u32_e32 v8, v8, v88
	v_ashrrev_i32_e32 v9, 31, v8
	v_lshlrev_b64 v[8:9], 9, v[8:9]
	v_lshl_add_u64 v[8:9], s[8:9], 0, v[8:9]
	v_lshl_add_u64 v[8:9], v[8:9], 0, v[80:81]
	v_mov_b32_e32 v83, v81
	v_lshl_add_u64 v[8:9], v[82:83], 2, v[8:9]
	v_cmp_lt_i32_e32 vcc, s58, v78
	s_waitcnt vmcnt(0)
	s_mov_b32 s0, 0xaaaaaaaa
	s_mov_b32 s1, 0xaaaaaaaa
	s_mov_b32 s2, 0xcccccccc
	s_mov_b32 s3, 0xcccccccc
	s_nop 1
	v_mov_b32_dpp v18, v4 quad_perm:[1,0,3,2] row_mask:0xf bank_mask:0xf
	v_mov_b32_dpp v19, v5 quad_perm:[1,0,3,2] row_mask:0xf bank_mask:0xf
	v_mov_b32_dpp v20, v6 quad_perm:[1,0,3,2] row_mask:0xf bank_mask:0xf
	v_mov_b32_dpp v21, v7 quad_perm:[1,0,3,2] row_mask:0xf bank_mask:0xf
	v_cndmask_b32_e64 v14, v4, v19, s[0:1]
	v_cndmask_b32_e64 v15, v18, v5, s[0:1]
	v_cndmask_b32_e64 v16, v6, v21, s[0:1]
	v_cndmask_b32_e64 v17, v20, v7, s[0:1]
	s_nop 1
	v_mov_b32_dpp v18, v14 quad_perm:[2,3,0,1] row_mask:0xf bank_mask:0xf
	v_mov_b32_dpp v19, v15 quad_perm:[2,3,0,1] row_mask:0xf bank_mask:0xf
	v_mov_b32_dpp v20, v16 quad_perm:[2,3,0,1] row_mask:0xf bank_mask:0xf
	v_mov_b32_dpp v21, v17 quad_perm:[2,3,0,1] row_mask:0xf bank_mask:0xf
	v_cndmask_b32_e64 v20, v14, v20, s[2:3]
	v_cndmask_b32_e64 v21, v15, v21, s[2:3]
	v_cndmask_b32_e64 v18, v18, v16, s[2:3]
	v_cndmask_b32_e64 v19, v19, v17, s[2:3]
	v_cvt_pk_bf16_f32 v14, v20, v21
	v_cvt_pk_bf16_f32 v15, v18, v19
	global_store_dwordx2 v[8:9], v[14:15], off
	s_nop 1
	v_mov_b32_dpp v18, v0 quad_perm:[1,0,3,2] row_mask:0xf bank_mask:0xf
	v_mov_b32_dpp v19, v1 quad_perm:[1,0,3,2] row_mask:0xf bank_mask:0xf
	v_mov_b32_dpp v20, v2 quad_perm:[1,0,3,2] row_mask:0xf bank_mask:0xf
	v_mov_b32_dpp v21, v3 quad_perm:[1,0,3,2] row_mask:0xf bank_mask:0xf
	v_cndmask_b32_e64 v14, v0, v19, s[0:1]
	v_cndmask_b32_e64 v15, v18, v1, s[0:1]
	v_cndmask_b32_e64 v16, v2, v21, s[0:1]
	v_cndmask_b32_e64 v17, v20, v3, s[0:1]
	s_nop 1
	v_mov_b32_dpp v18, v14 quad_perm:[2,3,0,1] row_mask:0xf bank_mask:0xf
	v_mov_b32_dpp v19, v15 quad_perm:[2,3,0,1] row_mask:0xf bank_mask:0xf
	v_mov_b32_dpp v20, v16 quad_perm:[2,3,0,1] row_mask:0xf bank_mask:0xf
	v_mov_b32_dpp v21, v17 quad_perm:[2,3,0,1] row_mask:0xf bank_mask:0xf
	v_cndmask_b32_e64 v20, v14, v20, s[2:3]
	v_cndmask_b32_e64 v21, v15, v21, s[2:3]
	v_cndmask_b32_e64 v18, v18, v16, s[2:3]
	v_cndmask_b32_e64 v19, v19, v17, s[2:3]
	v_cvt_pk_bf16_f32 v16, v20, v21
	v_cvt_pk_bf16_f32 v17, v18, v19
	global_store_dwordx2 v[8:9], v[16:17], off offset:32
	s_nop 1
	s_and_saveexec_b64 s[0:1], vcc
	s_xor_b64 s[0:1], exec, s[0:1]
	s_cbranch_execz .LBB0_807
	v_cmp_gt_u32_e32 vcc, s59, v78
	v_mov_b64_e32 v[8:9], 0
	s_and_saveexec_b64 s[2:3], vcc
	s_cbranch_execz .LBB0_798
	v_lshlrev_b32_e32 v8, 5, v78
	v_and_b32_e32 v8, 0xfff80, v8
	v_add3_u32 v8, v150, s83, v8
	v_ashrrev_i32_e32 v9, 31, v8
	v_readlane_b32 s4, v254, 14
	v_lshlrev_b64 v[8:9], 9, v[8:9]
	v_readlane_b32 s5, v254, 15
	s_nop 1
	v_lshl_add_u64 v[8:9], s[4:5], 0, v[8:9]
	v_lshl_add_u64 v[8:9], v[172:173], 2, v[8:9]
